# v18: DA QK^T section issues all K/Q fragment LDS reads of the tile up front (spare quads v240-255) with counted waits before each MFMA
# baseline (speedup 1.0000x reference)
; #define MFMA32(a, b, c) __builtin_amdgcn_mfma_f32_32x32x16_bf16((a), (b), (c), 0, 0, 0)
; DI int crow(int i, int hh) { return (i & 3) + 8 * (i >> 2) + 4 * hh; }
; DI f32x16 zero16() { f32x16 z; for (int i = 0; i < 16; i++) z[i] = 0.f; return z; }
; #define DA_FETCH(T) { const int ktn_ = min((T), nkt - 1); \
;       _Pragma("unroll") for (int i = 0; i < 2; i++) rk[i] = *(const u32x4*)(Kbase + (size_t)(ktn_ * 64 + i * 32) * 64); \
;       _Pragma("unroll") for (int i = 0; i < 4; i++) rv[i] = *(const u32x4*)(Vbase + (size_t)ktn_ * 8192 + (size_t)(i * 32) * 64); }
; DI void da_item(const Params& P, int layer, int b, int h, int qt, char* mb, char* smem) {
;     ...
;       DA_FETCH(kt + 2)
;       if (kt * 64 <= qw + 31) {
;         f32x16 s[2];
; #pragma unroll
;         for (int kb = 0; kb < 2; kb++) {
;           s[kb] = zero16();
; #pragma unroll
;           for (int ks = 0; ks < 4; ks++) {
;             const bf16x8 kf = *(const bf16x8*)(sK + (kb * 32 + r) * KS_ + ks * 16 + hh * 8);
;             const bf16x8 qf = *(const bf16x8*)(sQw + r * KS_ + ks * 16 + hh * 8);
;             s[kb] = MFMA32(kf, qf, s[kb]);
;           }
;         }
;         const bool nearb = (kt * 64 + 63 + 128 > qw);
;         float mx = -INFINITY;
;         if (nearb) {
; #pragma unroll
;           for (int kb = 0; kb < 2; kb++)
; #pragma unroll
;             for (int i = 0; i < 16; i++) {
;               const int dist = qp - (kt * 64 + kb * 32 + crow(i, hh));
;               const float bv = sbias[min(max(dist, 0), 128)];
;               float t = s[kb][i] * SC + bv;
;               t = (dist >= 0) ? t : -INFINITY;
;               s[kb][i] = t; mx = fmaxf(mx, t);
.LBB0_4120:
	s_add_i32 s4, s30, 2
	s_min_i32 s4, s4, s23
	s_lshl_b32 s44, s4, 6
	s_ashr_i32 s45, s44, 31
	s_lshl_b64 s[46:47], s[44:45], 7
	s_or_b32 s44, s44, 32
	s_ashr_i32 s45, s44, 31
	s_ashr_i32 s5, s4, 31
	v_lshl_add_u64 v[4:5], v[182:183], 0, s[46:47]
	s_lshl_b64 s[44:45], s[44:45], 7
	s_lshl_b64 s[4:5], s[4:5], 14
	v_lshl_add_u64 v[6:7], v[182:183], 0, s[44:45]
	global_load_dwordx4 v[114:117], v[4:5], off
	global_load_dwordx4 v[118:121], v[6:7], off
	v_lshl_add_u64 v[4:5], v[150:151], 0, s[4:5]
	v_add_co_u32_e32 v6, vcc, 0x1000, v4
	s_add_i32 s4, s10, 0xffffff41
	s_nop 0
	v_addc_co_u32_e32 v7, vcc, 0, v5, vcc
	global_load_dwordx4 v[122:125], v[4:5], off
	global_load_dwordx4 v[126:129], v[6:7], off
	v_add_co_u32_e32 v6, vcc, 0x2000, v4
	s_nop 1
	v_addc_co_u32_e32 v7, vcc, 0, v5, vcc
	v_add_co_u32_e32 v4, vcc, 0x3000, v4
	s_nop 1
	v_addc_co_u32_e32 v5, vcc, 0, v5, vcc
	global_load_dwordx4 v[130:133], v[6:7], off
	global_load_dwordx4 v[134:137], v[4:5], off
	v_cmp_le_i32_e32 vcc, s4, v214
	s_and_saveexec_b64 s[4:5], vcc
	s_cbranch_execz .LBB0_4128
	s_and_b32 s43, s30, 1
	s_mul_i32 s30, s43, 0x2400
	v_add_u32_e32 v3, s30, v215
	v_add_u32_e32 v16, v3, v211
	ds_read_b128 v[4:7], v16
	ds_read_b128 v[8:11], v212 offset:54272
	ds_read_b128 v[12:15], v212 offset:54304
	ds_read_b128 v[240:243], v16 offset:32
	v_add_u32_e32 v3, v3, v220
	v_cmp_le_i32_e32 vcc, s10, v210
	ds_read_b128 v[244:247], v16 offset:64
	ds_read_b128 v[184:187], v212 offset:54336
	ds_read_b128 v[228:231], v212 offset:54368
	ds_read_b128 v[248:251], v16 offset:96
	ds_read_b128 v[252:255], v3
	ds_read_b128 v[188:191], v3 offset:32
	ds_read_b128 v[232:235], v3 offset:64
	s_waitcnt lgkmcnt(9)
	v_mfma_f32_32x32x16_bf16 v[98:113], v[4:7], v[8:11], 0
	ds_read_b128 v[4:7], v3 offset:96
	s_waitcnt lgkmcnt(8)
	v_mfma_f32_32x32x16_bf16 v[98:113], v[240:243], v[12:15], v[98:113]
	s_waitcnt lgkmcnt(6)
	v_mfma_f32_32x32x16_bf16 v[98:113], v[244:247], v[184:187], v[98:113]
	s_waitcnt lgkmcnt(4)
	v_mfma_f32_32x32x16_bf16 v[98:113], v[248:251], v[228:231], v[98:113]
	s_waitcnt lgkmcnt(3)
	v_mfma_f32_32x32x16_bf16 v[82:97], v[252:255], v[8:11], 0
	s_waitcnt lgkmcnt(2)
	v_mfma_f32_32x32x16_bf16 v[82:97], v[188:191], v[12:15], v[82:97]
	s_waitcnt lgkmcnt(1)
	v_mfma_f32_32x32x16_bf16 v[82:97], v[232:235], v[184:187], v[82:97]
	s_waitcnt lgkmcnt(0)
	v_mfma_f32_32x32x16_bf16 v[82:97], v[4:7], v[228:231], v[82:97]
	s_and_saveexec_b64 s[30:31], vcc
	s_xor_b64 s[30:31], exec, s[30:31]
	s_cbranch_execz .LBB0_4123
	v_pk_fma_f32 v[4:5], v[98:99], s[20:21], v[138:139] op_sel_hi:[1,0,1]
	v_pk_fma_f32 v[6:7], v[100:101], s[20:21], v[138:139] op_sel_hi:[1,0,1]
	v_max3_f32 v3, v4, s36, v5
	v_max3_f32 v3, v3, v6, v7
	v_pk_fma_f32 v[8:9], v[102:103], s[20:21], v[138:139] op_sel_hi:[1,0,1]
	v_pk_fma_f32 v[10:11], v[104:105], s[20:21], v[138:139] op_sel_hi:[1,0,1]
	v_max3_f32 v3, v3, v8, v9
	v_max3_f32 v3, v3, v10, v11
	v_pk_fma_f32 v[12:13], v[106:107], s[20:21], v[138:139] op_sel_hi:[1,0,1]
	v_pk_fma_f32 v[14:15], v[108:109], s[20:21], v[138:139] op_sel_hi:[1,0,1]
	v_max3_f32 v3, v3, v12, v13
	v_max3_f32 v3, v3, v14, v15
	v_pk_fma_f32 v[16:17], v[110:111], s[20:21], v[138:139] op_sel_hi:[1,0,1]
	v_pk_fma_f32 v[184:185], v[112:113], s[20:21], v[138:139] op_sel_hi:[1,0,1]
	v_max3_f32 v3, v3, v16, v17
	v_max3_f32 v3, v3, v184, v185
	v_pk_fma_f32 v[186:187], v[82:83], s[20:21], v[138:139] op_sel_hi:[1,0,1]
	v_pk_fma_f32 v[188:189], v[84:85], s[20:21], v[138:139] op_sel_hi:[1,0,1]
	v_max3_f32 v3, v3, v186, v187
	v_max3_f32 v3, v3, v188, v189
	v_pk_fma_f32 v[190:191], v[86:87], s[20:21], v[138:139] op_sel_hi:[1,0,1]
	v_pk_fma_f32 v[192:193], v[88:89], s[20:21], v[138:139] op_sel_hi:[1,0,1]
	v_max3_f32 v3, v3, v190, v191
	v_max3_f32 v3, v3, v192, v193
	v_pk_fma_f32 v[200:201], v[90:91], s[20:21], v[138:139] op_sel_hi:[1,0,1]
	v_pk_fma_f32 v[198:199], v[92:93], s[20:21], v[138:139] op_sel_hi:[1,0,1]
	v_max3_f32 v3, v3, v200, v201
	v_max3_f32 v3, v3, v198, v199
	v_pk_fma_f32 v[196:197], v[94:95], s[20:21], v[138:139] op_sel_hi:[1,0,1]
	v_pk_fma_f32 v[194:195], v[96:97], s[20:21], v[138:139] op_sel_hi:[1,0,1]
	v_max3_f32 v3, v3, v196, v197
	v_max3_f32 v3, v3, v194, v195

; #define MFMA32(a, b, c) __builtin_amdgcn_mfma_f32_32x32x16_bf16((a), (b), (c), 0, 0, 0)
; DI int crow(int i, int hh) { return (i & 3) + 8 * (i >> 2) + 4 * hh; }
; DI f32x16 zero16() { f32x16 z; for (int i = 0; i < 16; i++) z[i] = 0.f; return z; }
; #define DA_FETCH(T) { const int ktn_ = min((T), nkt - 1); \
;       _Pragma("unroll") for (int i = 0; i < 2; i++) rk[i] = *(const u32x4*)(Kbase + (size_t)(ktn_ * 64 + i * 32) * 64); \
;       _Pragma("unroll") for (int i = 0; i < 4; i++) rv[i] = *(const u32x4*)(Vbase + (size_t)ktn_ * 8192 + (size_t)(i * 32) * 64); }
; DI void da_item(const Params& P, int layer, int b, int h, int qt, char* mb, char* smem) {
;     ...
;       DA_FETCH(kt + 2)
;       if (kt * 64 <= qw + 31) {
;         f32x16 s[2];
; #pragma unroll
;         for (int kb = 0; kb < 2; kb++) {
;           s[kb] = zero16();
; #pragma unroll
;           for (int ks = 0; ks < 4; ks++) {
;             const bf16x8 kf = *(const bf16x8*)(sK + (kb * 32 + r) * KS_ + ks * 16 + hh * 8);
;             const bf16x8 qf = *(const bf16x8*)(sQw + r * KS_ + ks * 16 + hh * 8);
;             s[kb] = MFMA32(kf, qf, s[kb]);
;           }
;         }
;         const bool nearb = (kt * 64 + 63 + 128 > qw);
;         float mx = -INFINITY;
;         if (nearb) {
; #pragma unroll
;           for (int kb = 0; kb < 2; kb++)
; #pragma unroll
;             for (int i = 0; i < 16; i++) {
;               const int dist = qp - (kt * 64 + kb * 32 + crow(i, hh));
;               const float bv = sbias[min(max(dist, 0), 128)];
;               float t = s[kb][i] * SC + bv;
;               t = (dist >= 0) ? t : -INFINITY;
;               s[kb][i] = t; mx = fmaxf(mx, t);
.LBB0_8079:
	s_add_i32 s4, s30, 2
	s_min_i32 s4, s4, s23
	s_lshl_b32 s44, s4, 6
	s_ashr_i32 s45, s44, 31
	s_lshl_b64 s[46:47], s[44:45], 7
	s_or_b32 s44, s44, 32
	s_ashr_i32 s45, s44, 31
	s_ashr_i32 s5, s4, 31
	v_lshl_add_u64 v[4:5], v[182:183], 0, s[46:47]
	s_lshl_b64 s[44:45], s[44:45], 7
	s_lshl_b64 s[4:5], s[4:5], 14
	v_lshl_add_u64 v[6:7], v[182:183], 0, s[44:45]
	global_load_dwordx4 v[114:117], v[4:5], off
	global_load_dwordx4 v[118:121], v[6:7], off
	v_lshl_add_u64 v[4:5], v[150:151], 0, s[4:5]
	v_add_co_u32_e32 v6, vcc, 0x1000, v4
	s_add_i32 s4, s10, 0xffffff41
	s_nop 0
	v_addc_co_u32_e32 v7, vcc, 0, v5, vcc
	global_load_dwordx4 v[122:125], v[4:5], off
	global_load_dwordx4 v[126:129], v[6:7], off
	v_add_co_u32_e32 v6, vcc, 0x2000, v4
	s_nop 1
	v_addc_co_u32_e32 v7, vcc, 0, v5, vcc
	v_add_co_u32_e32 v4, vcc, 0x3000, v4
	s_nop 1
	v_addc_co_u32_e32 v5, vcc, 0, v5, vcc
	global_load_dwordx4 v[130:133], v[6:7], off
	global_load_dwordx4 v[134:137], v[4:5], off
	v_cmp_le_i32_e32 vcc, s4, v215
	s_and_saveexec_b64 s[4:5], vcc
	s_cbranch_execz .LBB0_8087
	s_and_b32 s44, s30, 1
	s_mul_i32 s30, s44, 0x2400
	v_add_u32_e32 v3, s30, v216
	v_add_u32_e32 v16, v3, v212
	ds_read_b128 v[4:7], v16
	ds_read_b128 v[8:11], v213 offset:54272
	ds_read_b128 v[12:15], v213 offset:54304
	ds_read_b128 v[240:243], v16 offset:32
	v_add_u32_e32 v3, v3, v221
	v_cmp_le_i32_e32 vcc, s10, v211
	ds_read_b128 v[244:247], v16 offset:64
	ds_read_b128 v[184:187], v213 offset:54336
	ds_read_b128 v[228:231], v213 offset:54368
	ds_read_b128 v[248:251], v16 offset:96
	ds_read_b128 v[252:255], v3
	ds_read_b128 v[188:191], v3 offset:32
	ds_read_b128 v[232:235], v3 offset:64
	s_waitcnt lgkmcnt(9)
	v_mfma_f32_32x32x16_bf16 v[98:113], v[4:7], v[8:11], 0
	ds_read_b128 v[4:7], v3 offset:96
	s_waitcnt lgkmcnt(8)
	v_mfma_f32_32x32x16_bf16 v[98:113], v[240:243], v[12:15], v[98:113]
	s_waitcnt lgkmcnt(6)
	v_mfma_f32_32x32x16_bf16 v[98:113], v[244:247], v[184:187], v[98:113]
	s_waitcnt lgkmcnt(4)
	v_mfma_f32_32x32x16_bf16 v[98:113], v[248:251], v[228:231], v[98:113]
	s_waitcnt lgkmcnt(3)
	v_mfma_f32_32x32x16_bf16 v[82:97], v[252:255], v[8:11], 0
	s_waitcnt lgkmcnt(2)
	v_mfma_f32_32x32x16_bf16 v[82:97], v[188:191], v[12:15], v[82:97]
	s_waitcnt lgkmcnt(1)
	v_mfma_f32_32x32x16_bf16 v[82:97], v[232:235], v[184:187], v[82:97]
	s_waitcnt lgkmcnt(0)
	v_mfma_f32_32x32x16_bf16 v[82:97], v[4:7], v[228:231], v[82:97]
	s_and_saveexec_b64 s[30:31], vcc
	s_xor_b64 s[30:31], exec, s[30:31]
	s_cbranch_execz .LBB0_8082
	v_pk_fma_f32 v[4:5], v[98:99], s[20:21], v[138:139] op_sel_hi:[1,0,1]
	v_pk_fma_f32 v[6:7], v[100:101], s[20:21], v[138:139] op_sel_hi:[1,0,1]
	v_max3_f32 v3, v4, s37, v5
	v_max3_f32 v3, v3, v6, v7
	v_pk_fma_f32 v[8:9], v[102:103], s[20:21], v[138:139] op_sel_hi:[1,0,1]
	v_pk_fma_f32 v[10:11], v[104:105], s[20:21], v[138:139] op_sel_hi:[1,0,1]
	v_max3_f32 v3, v3, v8, v9
	v_max3_f32 v3, v3, v10, v11
	v_pk_fma_f32 v[12:13], v[106:107], s[20:21], v[138:139] op_sel_hi:[1,0,1]
	v_pk_fma_f32 v[14:15], v[108:109], s[20:21], v[138:139] op_sel_hi:[1,0,1]
	v_max3_f32 v3, v3, v12, v13
	v_max3_f32 v3, v3, v14, v15
	v_pk_fma_f32 v[16:17], v[110:111], s[20:21], v[138:139] op_sel_hi:[1,0,1]
	v_pk_fma_f32 v[184:185], v[112:113], s[20:21], v[138:139] op_sel_hi:[1,0,1]
	v_max3_f32 v3, v3, v16, v17
	v_max3_f32 v3, v3, v184, v185
	v_pk_fma_f32 v[186:187], v[82:83], s[20:21], v[138:139] op_sel_hi:[1,0,1]
	v_pk_fma_f32 v[188:189], v[84:85], s[20:21], v[138:139] op_sel_hi:[1,0,1]
	v_max3_f32 v3, v3, v186, v187
	v_max3_f32 v3, v3, v188, v189
	v_pk_fma_f32 v[190:191], v[86:87], s[20:21], v[138:139] op_sel_hi:[1,0,1]
	v_pk_fma_f32 v[192:193], v[88:89], s[20:21], v[138:139] op_sel_hi:[1,0,1]
	v_max3_f32 v3, v3, v190, v191
	v_max3_f32 v3, v3, v192, v193
	v_pk_fma_f32 v[200:201], v[90:91], s[20:21], v[138:139] op_sel_hi:[1,0,1]
	v_pk_fma_f32 v[198:199], v[92:93], s[20:21], v[138:139] op_sel_hi:[1,0,1]
	v_max3_f32 v3, v3, v200, v201
	v_max3_f32 v3, v3, v198, v199
	v_pk_fma_f32 v[196:197], v[94:95], s[20:21], v[138:139] op_sel_hi:[1,0,1]
	v_pk_fma_f32 v[194:195], v[96:97], s[20:21], v[138:139] op_sel_hi:[1,0,1]
	v_max3_f32 v3, v3, v196, v197
	v_max3_f32 v3, v3, v194, v195
